# UP: counted vmcnt(24) in first two K-phases after an epilogue (store drain hidden) + removed 2 drain waits
# speedup vs baseline: 1.0099x; 1.0099x over previous
; #define PG8_STAGE(bufoff, gbase) do { _Pragma("unroll") for (int _i = 0; _i < 2; ++_i) \
;         __builtin_amdgcn_global_load_lds((const unsigned*)((const char*)(gbase) + voff[_i]), (LAS unsigned*)(lds + (bufoff) + ldsw + _i * 8192), 16, 0, 0); } while (0)
; #define PG8_LDA(dst, b, h) do { _Pragma("unroll") for (int m = 0; m < 4; ++m) _Pragma("unroll") for (int k = 0; k < 2; ++k) dst[m][k] = *(const LAS bf16x8*)(lds + PG8_SA(b, h) + aoff + m * 2048 + k * 1024); } while (0)
; #define PG8_LDB(dst, b, h) do { _Pragma("unroll") for (int n = 0; n < 2; ++n) _Pragma("unroll") for (int k = 0; k < 2; ++k) dst[n][k] = *(const LAS bf16x8*)(lds + PG8_SB(b, h) + boff + n * 2048 + k * 1024); } while (0)
; #define PG8_MMA(ai, bj, At, Bt) do { __builtin_amdgcn_s_setprio(1); _Pragma("unroll") for (int m = 0; m < 4; ++m) _Pragma("unroll") for (int n = 0; n < 2; ++n) _Pragma("unroll") for (int k = 0; k < 2; ++k) \
;         acc[ai][bj][m][n] = __builtin_amdgcn_mfma_f32_16x16x32_bf16(Bt[n][k], At[m][k], acc[ai][bj][m][n], 0, 0, 0); __builtin_amdgcn_s_setprio(0); } while (0)
; #define PG8_WAIT_V(n) asm volatile("s_waitcnt vmcnt(" #n ")" ::: "memory")
; #define PG8_WAIT_L(n) asm volatile("s_waitcnt lgkmcnt(" #n ")" ::: "memory")
; #define PG8_BAR __builtin_amdgcn_s_barrier()
; #define PG8_SCHED __builtin_amdgcn_sched_barrier(0)
; template <int EPI> ...
;     ...
;         for (int t = 0; t < cnk; t += 2) {
;             const bool last = (t == cnk - 2);
;             const char* a1 = cA + (size_t)(t + 1) * kstep;
;             const char* a2 = last ? nA : cA + (size_t)(t + 2) * kstep; const char* b2 = last ? nB : cB + (size_t)(t + 2) * kstep;
;             const char* a3 = a2 + kstep; const char* b3 = b2 + kstep;
;             PG8_LDB(B0, 0, 0); PG8_LDB(B1, 0, 1); PG8_SCHED; PG8_LDA(At, 0, 0); PG8_STAGE(PG8_SA(1, 1), a1 + hstep);
;             PG8_WAIT_V(8); PG8_WAIT_L(0); PG8_BAR; PG8_MMA(0, 0, At, B0); PG8_MMA(0, 1, At, B1); PG8_BAR; PG8_SCHED;
;             PG8_LDA(At, 0, 1); PG8_STAGE(PG8_SB(0, 0), b2); PG8_STAGE(PG8_SB(0, 1), b2 + hstep); PG8_STAGE(PG8_SA(0, 0), a2);
.LBB0_970:
	ds_read_b128 v[38:41], v189
	ds_read_b128 v[42:45], v189 offset:1024
	ds_read_b128 v[46:49], v189 offset:2048
	ds_read_b128 v[50:53], v189 offset:3072
	ds_read_b128 v[54:57], v191
	ds_read_b128 v[58:61], v191 offset:1024
	ds_read_b128 v[66:69], v191 offset:2048
	ds_read_b128 v[70:73], v191 offset:3072
	s_add_u32 s58, s56, 0xfffc0080
	s_addc_u32 s59, s57, -1
	s_cmp_eq_u32 s83, 12
	s_cselect_b32 s61, s19, s59
	s_cselect_b32 s60, s49, s58
	s_cselect_b32 s59, s47, s63
	s_cselect_b32 s58, s55, s62
	v_lshl_add_u64 v[226:227], s[56:57], 0, v[206:207]
	s_add_i32 m0, s66, 0xc000
	ds_read_b128 v[162:165], v193
	ds_read_b128 v[166:169], v193 offset:1024
	ds_read_b128 v[170:173], v193 offset:2048
	ds_read_b128 v[174:177], v193 offset:3072
	ds_read_b128 v[178:181], v193 offset:4096
	ds_read_b128 v[214:217], v193 offset:5120
	ds_read_b128 v[218:221], v193 offset:6144
	ds_read_b128 v[222:225], v193 offset:7168
	global_load_lds_dwordx4 v[226:227], off
	v_lshl_add_u64 v[226:227], s[56:57], 0, v[208:209]
	s_add_i32 m0, s66, 0xe000
	s_nop 0
	global_load_lds_dwordx4 v[226:227], off
	s_cmp_lg_u32 s83, -2
	s_cbranch_scc1 .Lup_strict_0
	s_cmp_lt_u32 s70, 2
	s_cbranch_scc1 .Lup_strict_0
	s_waitcnt vmcnt(24)
	s_branch .Lup_wdone_0
.Lup_strict_0:
	s_waitcnt vmcnt(8)
.Lup_wdone_0:
	s_waitcnt lgkmcnt(0)
	s_barrier
	s_setprio 1
	s_waitcnt lgkmcnt(0)
	v_mfma_f32_16x16x32_bf16 v[150:153], v[38:41], v[162:165], v[150:153]
	v_mfma_f32_16x16x32_bf16 v[158:161], v[46:49], v[162:165], v[158:161]
	v_mfma_f32_16x16x32_bf16 v[134:137], v[38:41], v[170:173], v[134:137]
	v_mfma_f32_16x16x32_bf16 v[142:145], v[46:49], v[170:173], v[142:145]
	v_mfma_f32_16x16x32_bf16 v[118:121], v[38:41], v[178:181], v[118:121]
	v_mfma_f32_16x16x32_bf16 v[126:129], v[46:49], v[178:181], v[126:129]
	v_mfma_f32_16x16x32_bf16 v[110:113], v[38:41], v[218:221], v[110:113]
	v_mfma_f32_16x16x32_bf16 v[106:109], v[46:49], v[218:221], v[106:109]
	v_mfma_f32_16x16x32_bf16 v[150:153], v[42:45], v[166:169], v[150:153]
	v_mfma_f32_16x16x32_bf16 v[158:161], v[50:53], v[166:169], v[158:161]
	v_mfma_f32_16x16x32_bf16 v[134:137], v[42:45], v[174:177], v[134:137]
	v_mfma_f32_16x16x32_bf16 v[142:145], v[50:53], v[174:177], v[142:145]
	v_mfma_f32_16x16x32_bf16 v[118:121], v[42:45], v[214:217], v[118:121]
	v_mfma_f32_16x16x32_bf16 v[126:129], v[50:53], v[214:217], v[126:129]
	v_mfma_f32_16x16x32_bf16 v[110:113], v[42:45], v[222:225], v[110:113]
	v_mfma_f32_16x16x32_bf16 v[106:109], v[50:53], v[222:225], v[106:109]
	s_setprio 0
	s_setprio 1
	v_mfma_f32_16x16x32_bf16 v[146:149], v[54:57], v[162:165], v[146:149]
	v_mfma_f32_16x16x32_bf16 v[154:157], v[66:69], v[162:165], v[154:157]
	v_mfma_f32_16x16x32_bf16 v[130:133], v[54:57], v[170:173], v[130:133]
	v_mfma_f32_16x16x32_bf16 v[138:141], v[66:69], v[170:173], v[138:141]
	v_mfma_f32_16x16x32_bf16 v[114:117], v[54:57], v[178:181], v[114:117]
	v_mfma_f32_16x16x32_bf16 v[122:125], v[66:69], v[178:181], v[122:125]
	v_mfma_f32_16x16x32_bf16 v[102:105], v[54:57], v[218:221], v[102:105]
	v_mfma_f32_16x16x32_bf16 v[98:101], v[66:69], v[218:221], v[98:101]
	v_mfma_f32_16x16x32_bf16 v[146:149], v[58:61], v[166:169], v[146:149]
	v_mfma_f32_16x16x32_bf16 v[154:157], v[70:73], v[166:169], v[154:157]
	v_mfma_f32_16x16x32_bf16 v[130:133], v[58:61], v[174:177], v[130:133]
	v_mfma_f32_16x16x32_bf16 v[138:141], v[70:73], v[174:177], v[138:141]
	v_mfma_f32_16x16x32_bf16 v[114:117], v[58:61], v[214:217], v[114:117]
	v_mfma_f32_16x16x32_bf16 v[122:125], v[70:73], v[214:217], v[122:125]
	v_mfma_f32_16x16x32_bf16 v[102:105], v[58:61], v[222:225], v[102:105]
	v_mfma_f32_16x16x32_bf16 v[98:101], v[70:73], v[222:225], v[98:101]
	s_setprio 0
	s_barrier
	s_add_i32 s84, s75, s65
	v_lshl_add_u64 v[230:231], s[58:59], 0, v[194:195]
	s_mov_b32 m0, s84
	ds_read_b128 v[162:165], v193 offset:16384
	ds_read_b128 v[166:169], v193 offset:17408
	ds_read_b128 v[170:173], v193 offset:18432
	ds_read_b128 v[174:177], v193 offset:19456
	ds_read_b128 v[178:181], v193 offset:20480
	ds_read_b128 v[214:217], v193 offset:21504
	ds_read_b128 v[218:221], v193 offset:22528
	ds_read_b128 v[222:225], v193 offset:23552
	global_load_lds_dwordx4 v[230:231], off
	s_add_i32 m0, s84, 0x2000
	s_add_u32 s84, s58, 0x40000
	v_lshl_add_u64 v[232:233], s[58:59], 0, v[196:197]
	s_addc_u32 s85, s59, 0
	s_add_i32 s86, s76, s65
	global_load_lds_dwordx4 v[232:233], off
	v_lshl_add_u64 v[226:227], s[84:85], 0, v[194:195]
	s_mov_b32 m0, s86
	v_lshl_add_u64 v[234:235], s[60:61], 0, v[194:195]
	global_load_lds_dwordx4 v[226:227], off
	v_lshl_add_u64 v[226:227], s[84:85], 0, v[196:197]
	s_add_i32 m0, s86, 0x2000
	v_lshl_add_u64 v[236:237], s[60:61], 0, v[196:197]
	global_load_lds_dwordx4 v[226:227], off
	s_mov_b32 m0, s66
	s_nop 0
	global_load_lds_dwordx4 v[234:235], off
	s_mov_b32 m0, s67
	s_nop 0
	global_load_lds_dwordx4 v[236:237], off
	s_cmp_lg_u32 s83, -2
	s_cbranch_scc1 .Lup_strict_1
	s_cmp_lt_u32 s70, 2
	s_cbranch_scc1 .Lup_strict_1
	s_waitcnt vmcnt(24)
	s_branch .Lup_wdone_1

; #define PG8_STAGE(bufoff, gbase) do { _Pragma("unroll") for (int _i = 0; _i < 2; ++_i) \
;         __builtin_amdgcn_global_load_lds((const unsigned*)((const char*)(gbase) + voff[_i]), (LAS unsigned*)(lds + (bufoff) + ldsw + _i * 8192), 16, 0, 0); } while (0)
; #define PG8_LDA(dst, b, h) do { _Pragma("unroll") for (int m = 0; m < 4; ++m) _Pragma("unroll") for (int k = 0; k < 2; ++k) dst[m][k] = *(const LAS bf16x8*)(lds + PG8_SA(b, h) + aoff + m * 2048 + k * 1024); } while (0)
; #define PG8_LDB(dst, b, h) do { _Pragma("unroll") for (int n = 0; n < 2; ++n) _Pragma("unroll") for (int k = 0; k < 2; ++k) dst[n][k] = *(const LAS bf16x8*)(lds + PG8_SB(b, h) + boff + n * 2048 + k * 1024); } while (0)
; #define PG8_MMA(ai, bj, At, Bt) do { __builtin_amdgcn_s_setprio(1); _Pragma("unroll") for (int m = 0; m < 4; ++m) _Pragma("unroll") for (int n = 0; n < 2; ++n) _Pragma("unroll") for (int k = 0; k < 2; ++k) \
;         acc[ai][bj][m][n] = __builtin_amdgcn_mfma_f32_16x16x32_bf16(Bt[n][k], At[m][k], acc[ai][bj][m][n], 0, 0, 0); __builtin_amdgcn_s_setprio(0); } while (0)
; #define PG8_WAIT_V(n) asm volatile("s_waitcnt vmcnt(" #n ")" ::: "memory")
; #define PG8_WAIT_L(n) asm volatile("s_waitcnt lgkmcnt(" #n ")" ::: "memory")
; #define PG8_BAR __builtin_amdgcn_s_barrier()
; #define PG8_SCHED __builtin_amdgcn_sched_barrier(0)
; template <int EPI> ...
;     ...
;             PG8_LDA(At, 0, 1); PG8_STAGE(PG8_SB(0, 0), b2); PG8_STAGE(PG8_SB(0, 1), b2 + hstep); PG8_STAGE(PG8_SA(0, 0), a2);
;             PG8_WAIT_V(8); PG8_WAIT_L(0); PG8_BAR; PG8_MMA(1, 0, At, B0); PG8_MMA(1, 1, At, B1); PG8_BAR; PG8_SCHED;
;             PG8_LDB(B0, 1, 0); PG8_LDB(B1, 1, 1); PG8_SCHED; PG8_LDA(At, 1, 0); PG8_STAGE(PG8_SA(0, 1), a2 + hstep);
;             PG8_WAIT_V(8); PG8_WAIT_L(0); PG8_BAR; PG8_MMA(0, 0, At, B0); PG8_MMA(0, 1, At, B1); PG8_BAR; PG8_SCHED;
;             PG8_LDA(At, 1, 1); PG8_STAGE(PG8_SB(1, 0), b3); PG8_STAGE(PG8_SB(1, 1), b3 + hstep); PG8_STAGE(PG8_SA(1, 0), a3);
.Lup_wdone_1:
	s_waitcnt lgkmcnt(0)
	s_barrier
	s_setprio 1
	s_waitcnt lgkmcnt(0)
	v_mfma_f32_16x16x32_bf16 v[86:89], v[38:41], v[162:165], v[86:89]
	v_mfma_f32_16x16x32_bf16 v[94:97], v[46:49], v[162:165], v[94:97]
	v_mfma_f32_16x16x32_bf16 v[62:65], v[38:41], v[170:173], v[62:65]
	v_mfma_f32_16x16x32_bf16 v[78:81], v[46:49], v[170:173], v[78:81]
	v_mfma_f32_16x16x32_bf16 v[22:25], v[38:41], v[178:181], v[22:25]
	v_mfma_f32_16x16x32_bf16 v[30:33], v[46:49], v[178:181], v[30:33]
	v_mfma_f32_16x16x32_bf16 v[14:17], v[38:41], v[218:221], v[14:17]
	v_mfma_f32_16x16x32_bf16 v[10:13], v[46:49], v[218:221], v[10:13]
	v_mfma_f32_16x16x32_bf16 v[86:89], v[42:45], v[166:169], v[86:89]
	v_mfma_f32_16x16x32_bf16 v[94:97], v[50:53], v[166:169], v[94:97]
	v_mfma_f32_16x16x32_bf16 v[62:65], v[42:45], v[174:177], v[62:65]
	v_mfma_f32_16x16x32_bf16 v[78:81], v[50:53], v[174:177], v[78:81]
	v_mfma_f32_16x16x32_bf16 v[22:25], v[42:45], v[214:217], v[22:25]
	v_mfma_f32_16x16x32_bf16 v[30:33], v[50:53], v[214:217], v[30:33]
	v_mfma_f32_16x16x32_bf16 v[14:17], v[42:45], v[222:225], v[14:17]
	v_mfma_f32_16x16x32_bf16 v[10:13], v[50:53], v[222:225], v[10:13]
	s_setprio 0
	s_setprio 1
	v_mfma_f32_16x16x32_bf16 v[34:37], v[54:57], v[170:173], v[34:37]
	v_mfma_f32_16x16x32_bf16 v[18:21], v[54:57], v[178:181], v[18:21]
	v_mfma_f32_16x16x32_bf16 v[26:29], v[66:69], v[178:181], v[26:29]
	v_mfma_f32_16x16x32_bf16 v[6:9], v[54:57], v[218:221], v[6:9]
	v_mfma_f32_16x16x32_bf16 v[2:5], v[66:69], v[218:221], v[2:5]
	v_mfma_f32_16x16x32_bf16 v[38:41], v[54:57], v[162:165], v[82:85]
	v_mfma_f32_16x16x32_bf16 v[42:45], v[66:69], v[162:165], v[90:93]
	v_mfma_f32_16x16x32_bf16 v[34:37], v[58:61], v[174:177], v[34:37]
	v_mfma_f32_16x16x32_bf16 v[46:49], v[66:69], v[170:173], v[74:77]
	v_mfma_f32_16x16x32_bf16 v[18:21], v[58:61], v[214:217], v[18:21]
	v_mfma_f32_16x16x32_bf16 v[26:29], v[70:73], v[214:217], v[26:29]
	v_mfma_f32_16x16x32_bf16 v[6:9], v[58:61], v[222:225], v[6:9]
	v_mfma_f32_16x16x32_bf16 v[2:5], v[70:73], v[222:225], v[2:5]
	v_mfma_f32_16x16x32_bf16 v[38:41], v[58:61], v[166:169], v[38:41]
	v_mfma_f32_16x16x32_bf16 v[42:45], v[70:73], v[166:169], v[42:45]
	v_mfma_f32_16x16x32_bf16 v[46:49], v[70:73], v[174:177], v[46:49]
	s_setprio 0
	s_barrier
	s_add_i32 s84, 0, 0x18000
	s_add_i32 s85, 0, 0x1c000
	v_add_u32_e32 v66, s84, v183
	v_add_u32_e32 v74, s85, v183
	ds_read_b128 v[50:53], v66
	ds_read_b128 v[54:57], v66 offset:1024
	ds_read_b128 v[58:61], v66 offset:2048
	ds_read_b128 v[66:69], v66 offset:3072
	ds_read_b128 v[70:73], v74
	ds_read_b128 v[162:165], v74 offset:1024
	ds_read_b128 v[166:169], v74 offset:2048
	ds_read_b128 v[170:173], v74 offset:3072
	s_add_u32 s60, s60, 0x40000
	s_addc_u32 s61, s61, 0
	s_mov_b32 m0, s68
	v_lshl_add_u64 v[226:227], s[60:61], 0, v[194:195]
	ds_read_b128 v[74:77], v193 offset:32768
	ds_read_b128 v[82:85], v193 offset:33792
	ds_read_b128 v[90:93], v193 offset:34816
	ds_read_b128 v[174:177], v193 offset:35840
	ds_read_b128 v[178:181], v193 offset:36864
	ds_read_b128 v[214:217], v193 offset:37888
	ds_read_b128 v[218:221], v193 offset:38912
	ds_read_b128 v[222:225], v193 offset:39936
	global_load_lds_dwordx4 v[226:227], off
	v_lshl_add_u64 v[226:227], s[60:61], 0, v[196:197]
	s_mov_b32 m0, s69
	s_nop 0
	global_load_lds_dwordx4 v[226:227], off
	s_waitcnt vmcnt(8)
	s_waitcnt lgkmcnt(0)
	s_barrier
	s_setprio 1
	s_waitcnt lgkmcnt(0)
	v_mfma_f32_16x16x32_bf16 v[150:153], v[50:53], v[74:77], v[150:153]
	v_mfma_f32_16x16x32_bf16 v[158:161], v[58:61], v[74:77], v[158:161]
	v_mfma_f32_16x16x32_bf16 v[134:137], v[50:53], v[90:93], v[134:137]
	v_mfma_f32_16x16x32_bf16 v[142:145], v[58:61], v[90:93], v[142:145]
	v_mfma_f32_16x16x32_bf16 v[118:121], v[50:53], v[178:181], v[118:121]
	v_mfma_f32_16x16x32_bf16 v[126:129], v[58:61], v[178:181], v[126:129]
	v_mfma_f32_16x16x32_bf16 v[110:113], v[50:53], v[218:221], v[110:113]
	v_mfma_f32_16x16x32_bf16 v[106:109], v[58:61], v[218:221], v[106:109]
	v_mfma_f32_16x16x32_bf16 v[150:153], v[54:57], v[82:85], v[150:153]
	v_mfma_f32_16x16x32_bf16 v[158:161], v[66:69], v[82:85], v[158:161]
	v_mfma_f32_16x16x32_bf16 v[134:137], v[54:57], v[174:177], v[134:137]
	v_mfma_f32_16x16x32_bf16 v[142:145], v[66:69], v[174:177], v[142:145]
	v_mfma_f32_16x16x32_bf16 v[118:121], v[54:57], v[214:217], v[118:121]
	v_mfma_f32_16x16x32_bf16 v[126:129], v[66:69], v[214:217], v[126:129]
	v_mfma_f32_16x16x32_bf16 v[110:113], v[54:57], v[222:225], v[110:113]
	v_mfma_f32_16x16x32_bf16 v[106:109], v[66:69], v[222:225], v[106:109]
	s_setprio 0
	s_setprio 1
	v_mfma_f32_16x16x32_bf16 v[146:149], v[70:73], v[74:77], v[146:149]
	v_mfma_f32_16x16x32_bf16 v[74:77], v[166:169], v[74:77], v[154:157]
	v_mfma_f32_16x16x32_bf16 v[154:157], v[170:173], v[82:85], v[74:77]
	v_mfma_f32_16x16x32_bf16 v[74:77], v[70:73], v[90:93], v[130:133]
	v_mfma_f32_16x16x32_bf16 v[130:133], v[162:165], v[174:177], v[74:77]
	v_mfma_f32_16x16x32_bf16 v[74:77], v[166:169], v[90:93], v[138:141]
	v_mfma_f32_16x16x32_bf16 v[138:141], v[170:173], v[174:177], v[74:77]
	v_mfma_f32_16x16x32_bf16 v[74:77], v[70:73], v[178:181], v[114:117]
	v_mfma_f32_16x16x32_bf16 v[114:117], v[162:165], v[214:217], v[74:77]
	v_mfma_f32_16x16x32_bf16 v[74:77], v[166:169], v[178:181], v[122:125]
	v_mfma_f32_16x16x32_bf16 v[122:125], v[170:173], v[214:217], v[74:77]
	v_mfma_f32_16x16x32_bf16 v[74:77], v[70:73], v[218:221], v[102:105]
	v_mfma_f32_16x16x32_bf16 v[102:105], v[162:165], v[222:225], v[74:77]
	v_mfma_f32_16x16x32_bf16 v[74:77], v[166:169], v[218:221], v[98:101]
	v_mfma_f32_16x16x32_bf16 v[146:149], v[162:165], v[82:85], v[146:149]
	v_mfma_f32_16x16x32_bf16 v[98:101], v[170:173], v[222:225], v[74:77]
	s_setprio 0
	s_barrier
; #define PG8_STAGE(bufoff, gbase) do { _Pragma("unroll") for (int _i = 0; _i < 2; ++_i) \
;         __builtin_amdgcn_global_load_lds((const unsigned*)((const char*)(gbase) + voff[_i]), (LAS unsigned*)(lds + (bufoff) + ldsw + _i * 8192), 16, 0, 0); } while (0)
; #define PG8_LDA(dst, b, h) do { _Pragma("unroll") for (int m = 0; m < 4; ++m) _Pragma("unroll") for (int k = 0; k < 2; ++k) dst[m][k] = *(const LAS bf16x8*)(lds + PG8_SA(b, h) + aoff + m * 2048 + k * 1024); } while (0)
; #define PG8_MMA(ai, bj, At, Bt) do { __builtin_amdgcn_s_setprio(1); _Pragma("unroll") for (int m = 0; m < 4; ++m) _Pragma("unroll") for (int n = 0; n < 2; ++n) _Pragma("unroll") for (int k = 0; k < 2; ++k) \
;         acc[ai][bj][m][n] = __builtin_amdgcn_mfma_f32_16x16x32_bf16(Bt[n][k], At[m][k], acc[ai][bj][m][n], 0, 0, 0); __builtin_amdgcn_s_setprio(0); } while (0)
; #define PG8_WAIT_V(n) asm volatile("s_waitcnt vmcnt(" #n ")" ::: "memory")
; #define PG8_WAIT_L(n) asm volatile("s_waitcnt lgkmcnt(" #n ")" ::: "memory")
; #define PG8_BAR __builtin_amdgcn_s_barrier()
; #define PG8_SCHED __builtin_amdgcn_sched_barrier(0)
; template <int EPI> ...
;     ...
;             PG8_LDA(At, 1, 1); PG8_STAGE(PG8_SB(1, 0), b3); PG8_STAGE(PG8_SB(1, 1), b3 + hstep); PG8_STAGE(PG8_SA(1, 0), a3);
;             PG8_WAIT_V(8); PG8_WAIT_L(0); PG8_BAR; PG8_MMA(1, 0, At, B0); PG8_MMA(1, 1, At, B1); PG8_BAR; PG8_SCHED;
;         }
;         if (wr == 0) PG8_BAR;
	s_add_i32 s60, s84, s65
	v_lshl_add_u64 v[82:83], v[230:231], 0, s[26:27]
	s_mov_b32 m0, s60
	s_nop 0
	ds_read_b128 v[74:77], v193 offset:49152
	ds_read_b128 v[90:93], v193 offset:50176
	ds_read_b128 v[174:177], v193 offset:51200
	ds_read_b128 v[178:181], v193 offset:52224
	ds_read_b128 v[214:217], v193 offset:53248
	ds_read_b128 v[218:221], v193 offset:54272
	ds_read_b128 v[222:225], v193 offset:55296
	ds_read_b128 v[226:229], v193 offset:56320
	global_load_lds_dwordx4 v[82:83], off
	s_add_i32 m0, s60, 0x2000
	s_add_u32 s58, s58, 0x40080
	v_lshl_add_u64 v[82:83], v[232:233], 0, s[26:27]
	s_addc_u32 s59, s59, 0
	s_add_i32 s60, s85, s65
	global_load_lds_dwordx4 v[82:83], off
	v_lshl_add_u64 v[82:83], s[58:59], 0, v[194:195]
	s_mov_b32 m0, s60
	s_nop 0
	global_load_lds_dwordx4 v[82:83], off
	v_lshl_add_u64 v[82:83], s[58:59], 0, v[196:197]
	s_add_i32 m0, s60, 0x2000
	s_nop 0
	global_load_lds_dwordx4 v[82:83], off
	v_lshl_add_u64 v[82:83], v[234:235], 0, s[26:27]
	s_mov_b32 m0, s72
	s_nop 0
	global_load_lds_dwordx4 v[82:83], off
	v_lshl_add_u64 v[82:83], v[236:237], 0, s[26:27]
	s_mov_b32 m0, s73
	s_nop 0
	global_load_lds_dwordx4 v[82:83], off
	s_waitcnt vmcnt(8)
	s_waitcnt lgkmcnt(0)
	s_barrier
	s_setprio 1
	s_waitcnt lgkmcnt(0)
	v_mfma_f32_16x16x32_bf16 v[82:85], v[50:53], v[74:77], v[86:89]
	v_mfma_f32_16x16x32_bf16 v[86:89], v[54:57], v[90:93], v[82:85]
	v_mfma_f32_16x16x32_bf16 v[82:85], v[58:61], v[74:77], v[94:97]
	v_mfma_f32_16x16x32_bf16 v[62:65], v[50:53], v[174:177], v[62:65]
	v_mfma_f32_16x16x32_bf16 v[78:81], v[58:61], v[174:177], v[78:81]
	v_mfma_f32_16x16x32_bf16 v[22:25], v[50:53], v[214:217], v[22:25]
	v_mfma_f32_16x16x32_bf16 v[30:33], v[58:61], v[214:217], v[30:33]
	v_mfma_f32_16x16x32_bf16 v[14:17], v[50:53], v[222:225], v[14:17]
	v_mfma_f32_16x16x32_bf16 v[10:13], v[58:61], v[222:225], v[10:13]
	v_mfma_f32_16x16x32_bf16 v[94:97], v[66:69], v[90:93], v[82:85]
	v_mfma_f32_16x16x32_bf16 v[62:65], v[54:57], v[178:181], v[62:65]
	v_mfma_f32_16x16x32_bf16 v[78:81], v[66:69], v[178:181], v[78:81]
	v_mfma_f32_16x16x32_bf16 v[22:25], v[54:57], v[218:221], v[22:25]
	v_mfma_f32_16x16x32_bf16 v[30:33], v[66:69], v[218:221], v[30:33]
	v_mfma_f32_16x16x32_bf16 v[14:17], v[54:57], v[226:229], v[14:17]
	v_mfma_f32_16x16x32_bf16 v[10:13], v[66:69], v[226:229], v[10:13]
	s_setprio 0
	s_setprio 1
	v_mfma_f32_16x16x32_bf16 v[38:41], v[70:73], v[74:77], v[38:41]
	v_mfma_f32_16x16x32_bf16 v[82:85], v[162:165], v[90:93], v[38:41]
	v_mfma_f32_16x16x32_bf16 v[38:41], v[166:169], v[74:77], v[42:45]
	v_mfma_f32_16x16x32_bf16 v[90:93], v[170:173], v[90:93], v[38:41]
	v_mfma_f32_16x16x32_bf16 v[34:37], v[70:73], v[174:177], v[34:37]
	v_mfma_f32_16x16x32_bf16 v[38:41], v[166:169], v[174:177], v[46:49]
	v_mfma_f32_16x16x32_bf16 v[18:21], v[70:73], v[214:217], v[18:21]
	v_mfma_f32_16x16x32_bf16 v[26:29], v[166:169], v[214:217], v[26:29]
	v_mfma_f32_16x16x32_bf16 v[6:9], v[70:73], v[222:225], v[6:9]
	v_mfma_f32_16x16x32_bf16 v[2:5], v[166:169], v[222:225], v[2:5]
	v_mfma_f32_16x16x32_bf16 v[34:37], v[162:165], v[178:181], v[34:37]
	v_mfma_f32_16x16x32_bf16 v[74:77], v[170:173], v[178:181], v[38:41]
	v_mfma_f32_16x16x32_bf16 v[18:21], v[162:165], v[218:221], v[18:21]
	v_mfma_f32_16x16x32_bf16 v[26:29], v[170:173], v[218:221], v[26:29]
	v_mfma_f32_16x16x32_bf16 v[6:9], v[162:165], v[226:229], v[6:9]
	v_mfma_f32_16x16x32_bf16 v[2:5], v[170:173], v[226:229], v[2:5]
	s_setprio 0
	s_barrier
	s_add_i32 s83, s83, 2
	s_add_u32 s56, s56, 0x100
	s_addc_u32 s57, s57, 0
	s_add_u32 s62, s62, 0x100
	s_addc_u32 s63, s63, 0
	s_cmp_gt_u32 s83, 13
	s_cbranch_scc0 .LBB0_970
	s_and_b64 vcc, exec, s[28:29]
	s_cbranch_vccz .LBB0_973
	s_barrier
